# HG1/HG3 load_meta: the 8 per-token blocks' MSSQ/row loads issued up front (one round trip instead of ~16), V-part MSSQ wait moved behind its row loads
# speedup vs baseline: 1.0019x; 1.0011x over previous
.LBB0_1249:
	v_and_b32_e32 v0, 0x7e, v66
	v_or_b32_e32 v0, s62, v0
	v_lshlrev_b32_e32 v64, 2, v0
	s_waitcnt lgkmcnt(0)
	global_load_dwordx2 v[0:1], v64, s[38:39]
	v_add_u32_e32 v8, s33, v67
	v_readlane_b32 s18, v254, 14
	v_ashrrev_i32_e32 v2, 6, v8
	v_readlane_b32 s19, v254, 15
	v_mov_b32_e32 v10, 0
	v_cmp_gt_i32_e64 s[14:15], 2, v2
	v_lshlrev_b32_e32 v4, 3, v2
	v_lshl_add_u64 v[2:3], s[18:19], 0, v[64:65]
	v_mov_b32_e32 v11, 0
	s_and_saveexec_b64 s[98:99], s[14:15]
	s_cbranch_execz .Lhgm_hg1
	v_readlane_b32 s100, v254, 11
	v_readlane_b32 s101, v254, 12
	v_mov_b32_e32 v214, v4
	v_ashrrev_i32_e32 v215, 31, v4
	s_nop 0
	v_lshl_add_u64 v[216:217], v[214:215], 2, s[100:101]
	global_load_dwordx4 v[218:221], v[216:217], off
	global_load_dwordx4 v[222:225], v[216:217], off offset:16
	v_lshlrev_b64 v[214:215], 14, v[214:215]
	v_lshl_add_u64 v[214:215], v[2:3], 0, v[214:215]
	s_mov_b64 s[100:101], 0x1000
	v_lshl_add_u64 v[216:217], v[214:215], 0, s[100:101]
	s_mov_b64 s[100:101], 0x4000
	global_load_dwordx2 v[226:227], v[216:217], off
	v_lshl_add_u64 v[216:217], v[216:217], 0, s[100:101]
	global_load_dwordx2 v[228:229], v[216:217], off
	v_lshl_add_u64 v[216:217], v[216:217], 0, s[100:101]
	global_load_dwordx2 v[230:231], v[216:217], off
	v_lshl_add_u64 v[216:217], v[216:217], 0, s[100:101]
	global_load_dwordx2 v[232:233], v[216:217], off
	v_lshl_add_u64 v[216:217], v[216:217], 0, s[100:101]
	global_load_dwordx2 v[234:235], v[216:217], off
	v_lshl_add_u64 v[216:217], v[216:217], 0, s[100:101]
	global_load_dwordx2 v[236:237], v[216:217], off
	v_lshl_add_u64 v[216:217], v[216:217], 0, s[100:101]
	global_load_dwordx2 v[238:239], v[216:217], off
	v_lshl_add_u64 v[216:217], v[216:217], 0, s[100:101]
	global_load_dwordx2 v[240:241], v[216:217], off
.Lhgm_hg1:
	s_or_b64 exec, exec, s[98:99]
	s_waitcnt vmcnt(0)
	v_sub_f32_e32 v7, 1.0, v0
	v_sub_f32_e32 v6, 1.0, v1
	s_and_saveexec_b64 s[78:79], s[14:15]
	s_cbranch_execz .LBB0_1251
	v_readlane_b32 s18, v254, 11
	v_ashrrev_i32_e32 v5, 31, v4
	v_readlane_b32 s19, v254, 12
	s_nop 1
	v_lshl_add_u64 v[12:13], v[4:5], 2, s[18:19]
	s_waitcnt vmcnt(0)
	v_mov_b32_e32 v9, v218
	v_lshlrev_b64 v[12:13], 14, v[4:5]
	v_lshl_add_u64 v[12:13], v[2:3], 0, v[12:13]
	s_waitcnt vmcnt(0)
	v_fmamk_f32 v9, v9, 0x3a800000, v201
	v_cmp_gt_f32_e32 vcc, s83, v9
	v_mul_f32_e32 v11, 0x4b800000, v9
	s_nop 0
	v_cndmask_b32_e32 v9, v9, v11, vcc
	v_rsq_f32_e32 v9, v9
	s_nop 0
	v_mul_f32_e32 v11, 0x45800000, v9
	v_cndmask_b32_e32 v9, v9, v11, vcc
	v_add_co_u32_e32 v12, vcc, 0x1000, v12
	s_nop 1
	v_addc_co_u32_e32 v13, vcc, 0, v13, vcc
	v_mov_b64_e32 v[12:13], v[226:227]
	s_waitcnt vmcnt(0)
	v_mul_f32_e32 v5, v12, v9
	v_mul_f32_e32 v5, 0xbfb8aa3b, v5
	v_exp_f32_e32 v5, v5
	v_mul_f32_e32 v9, v13, v9
	v_mul_f32_e32 v9, 0xbfb8aa3b, v9
	v_exp_f32_e32 v9, v9
	v_add_f32_e32 v5, 1.0, v5
	v_rcp_f32_e32 v5, v5
	v_add_f32_e32 v9, 1.0, v9
	v_rcp_f32_e32 v9, v9
	v_fma_f32 v5, v7, v5, v0
	v_cmp_gt_f32_e32 vcc, s83, v5
	v_fma_f32 v9, v6, v9, v1
	s_nop 0
	v_cndmask_b32_e64 v11, 0, 32, vcc
	v_ldexp_f32 v5, v5, v11
	v_log_f32_e32 v5, v5
	s_nop 0
	v_mul_f32_e32 v11, 0x3f317217, v5
	v_fma_f32 v11, v5, s84, -v11
	v_fmac_f32_e32 v11, 0x3377d1cf, v5
	v_fmac_f32_e32 v11, 0x3f317217, v5
	v_cmp_lt_f32_e64 s[18:19], |v5|, s85
	s_nop 1
	v_cndmask_b32_e64 v5, v5, v11, s[18:19]
	v_cndmask_b32_e32 v11, 0, v202, vcc
	v_cmp_gt_f32_e32 vcc, s83, v9
	v_sub_f32_e32 v5, v5, v11
	v_cvt_f16_f32_e32 v5, v5
	v_cndmask_b32_e64 v11, 0, 32, vcc
	v_ldexp_f32 v9, v9, v11
	v_log_f32_e32 v9, v9
	s_nop 0
	v_mul_f32_e32 v11, 0x3f317217, v9
	v_fma_f32 v11, v9, s84, -v11
	v_fmac_f32_e32 v11, 0x3377d1cf, v9
	v_fmac_f32_e32 v11, 0x3f317217, v9
	v_cmp_lt_f32_e64 s[18:19], |v9|, s85
	s_nop 1
	v_cndmask_b32_e64 v9, v9, v11, s[18:19]
	v_cndmask_b32_e32 v11, 0, v202, vcc
	v_sub_f32_e32 v9, v9, v11
	v_cvt_f16_f32_sdwa v9, v9 dst_sel:WORD_1 dst_unused:UNUSED_PAD src0_sel:DWORD
	s_nop 0
	v_or_b32_e32 v11, v9, v5
.LBB0_1251:
	s_or_b64 exec, exec, s[78:79]
	s_and_saveexec_b64 s[78:79], s[14:15]
	s_cbranch_execz .LBB0_1253
	v_or_b32_e32 v12, 1, v4
	v_readlane_b32 s18, v254, 11
	v_ashrrev_i32_e32 v13, 31, v12
	v_readlane_b32 s19, v254, 12
	s_nop 1
	v_lshl_add_u64 v[14:15], v[12:13], 2, s[18:19]
	s_waitcnt vmcnt(0)
	v_mov_b32_e32 v5, v219
	v_lshlrev_b64 v[12:13], 14, v[12:13]
	v_lshl_add_u64 v[12:13], v[2:3], 0, v[12:13]
	s_waitcnt vmcnt(0)
	v_fmamk_f32 v5, v5, 0x3a800000, v201
	v_cmp_gt_f32_e32 vcc, s83, v5
	v_mul_f32_e32 v9, 0x4b800000, v5
	s_nop 0
	v_cndmask_b32_e32 v5, v5, v9, vcc
	v_rsq_f32_e32 v5, v5
	s_nop 0
	v_mul_f32_e32 v9, 0x45800000, v5
	v_cndmask_b32_e32 v5, v5, v9, vcc
	v_add_co_u32_e32 v12, vcc, 0x1000, v12
	s_nop 1
	v_addc_co_u32_e32 v13, vcc, 0, v13, vcc
	v_mov_b64_e32 v[12:13], v[228:229]
	s_waitcnt vmcnt(0)
	v_mul_f32_e32 v9, v12, v5
	v_mul_f32_e32 v9, 0xbfb8aa3b, v9
	v_exp_f32_e32 v9, v9
	v_mul_f32_e32 v5, v13, v5
	v_mul_f32_e32 v5, 0xbfb8aa3b, v5
	v_exp_f32_e32 v5, v5
	v_add_f32_e32 v9, 1.0, v9
	v_rcp_f32_e32 v9, v9
	v_add_f32_e32 v5, 1.0, v5
	v_rcp_f32_e32 v5, v5
	v_fma_f32 v9, v7, v9, v0
	v_cmp_gt_f32_e32 vcc, s83, v9
	v_fma_f32 v5, v6, v5, v1
	s_nop 0
	v_cndmask_b32_e64 v10, 0, 32, vcc
	v_ldexp_f32 v9, v9, v10
	v_log_f32_e32 v9, v9
	s_nop 0
	v_mul_f32_e32 v10, 0x3f317217, v9
	v_fma_f32 v10, v9, s84, -v10
	v_fmac_f32_e32 v10, 0x3377d1cf, v9
	v_fmac_f32_e32 v10, 0x3f317217, v9
	v_cmp_lt_f32_e64 s[18:19], |v9|, s85
	s_nop 1
	v_cndmask_b32_e64 v9, v9, v10, s[18:19]
	v_cndmask_b32_e32 v10, 0, v202, vcc
	v_cmp_gt_f32_e32 vcc, s83, v5
	v_sub_f32_e32 v9, v9, v10
	v_cvt_f16_f32_e32 v9, v9
	v_cndmask_b32_e64 v10, 0, 32, vcc
	v_ldexp_f32 v5, v5, v10
	v_log_f32_e32 v5, v5
	s_nop 0
	v_mul_f32_e32 v10, 0x3f317217, v5
	v_fma_f32 v10, v5, s84, -v10
	v_fmac_f32_e32 v10, 0x3377d1cf, v5
	v_fmac_f32_e32 v10, 0x3f317217, v5
	v_cmp_lt_f32_e64 s[18:19], |v5|, s85
	s_nop 1
	v_cndmask_b32_e64 v5, v5, v10, s[18:19]
	v_cndmask_b32_e32 v10, 0, v202, vcc
	v_sub_f32_e32 v5, v5, v10
	v_cvt_f16_f32_sdwa v5, v5 dst_sel:WORD_1 dst_unused:UNUSED_PAD src0_sel:DWORD
	s_nop 0
	v_or_b32_e32 v10, v5, v9
.LBB0_1253:
	s_or_b64 exec, exec, s[78:79]
	v_mov_b32_e32 v12, 0
	v_mov_b32_e32 v13, 0
	s_and_saveexec_b64 s[78:79], s[14:15]
	s_cbranch_execz .LBB0_1255
	v_or_b32_e32 v14, 2, v4
	v_readlane_b32 s18, v254, 11
	v_ashrrev_i32_e32 v15, 31, v14
	v_readlane_b32 s19, v254, 12
	s_nop 1
	v_lshl_add_u64 v[16:17], v[14:15], 2, s[18:19]
	s_waitcnt vmcnt(0)
	v_mov_b32_e32 v5, v220
	v_lshlrev_b64 v[14:15], 14, v[14:15]
	v_lshl_add_u64 v[14:15], v[2:3], 0, v[14:15]
	s_waitcnt vmcnt(0)
	v_fmamk_f32 v5, v5, 0x3a800000, v201
	v_cmp_gt_f32_e32 vcc, s83, v5
	v_mul_f32_e32 v9, 0x4b800000, v5
	s_nop 0
	v_cndmask_b32_e32 v5, v5, v9, vcc
	v_rsq_f32_e32 v5, v5
	s_nop 0
	v_mul_f32_e32 v9, 0x45800000, v5
	v_cndmask_b32_e32 v5, v5, v9, vcc
	v_add_co_u32_e32 v14, vcc, 0x1000, v14
	s_nop 1
	v_addc_co_u32_e32 v15, vcc, 0, v15, vcc
	v_mov_b64_e32 v[14:15], v[230:231]
	s_waitcnt vmcnt(0)
	v_mul_f32_e32 v9, v14, v5
	v_mul_f32_e32 v9, 0xbfb8aa3b, v9
	v_exp_f32_e32 v9, v9
	v_mul_f32_e32 v5, v15, v5
	v_mul_f32_e32 v5, 0xbfb8aa3b, v5
	v_exp_f32_e32 v5, v5
	v_add_f32_e32 v9, 1.0, v9
	v_rcp_f32_e32 v9, v9
	v_add_f32_e32 v5, 1.0, v5
	v_rcp_f32_e32 v5, v5
	v_fma_f32 v9, v7, v9, v0
	v_cmp_gt_f32_e32 vcc, s83, v9
	v_fma_f32 v5, v6, v5, v1
	s_nop 0
	v_cndmask_b32_e64 v13, 0, 32, vcc
	v_ldexp_f32 v9, v9, v13
	v_log_f32_e32 v9, v9
	s_nop 0
	v_mul_f32_e32 v13, 0x3f317217, v9
	v_fma_f32 v13, v9, s84, -v13
	v_fmac_f32_e32 v13, 0x3377d1cf, v9
	v_fmac_f32_e32 v13, 0x3f317217, v9
	v_cmp_lt_f32_e64 s[18:19], |v9|, s85
	s_nop 1
	v_cndmask_b32_e64 v9, v9, v13, s[18:19]
	v_cndmask_b32_e32 v13, 0, v202, vcc
	v_cmp_gt_f32_e32 vcc, s83, v5
	v_sub_f32_e32 v9, v9, v13
	v_cvt_f16_f32_e32 v9, v9
	v_cndmask_b32_e64 v13, 0, 32, vcc
	v_ldexp_f32 v5, v5, v13
	v_log_f32_e32 v5, v5
	s_nop 0
	v_mul_f32_e32 v13, 0x3f317217, v5
	v_fma_f32 v13, v5, s84, -v13
	v_fmac_f32_e32 v13, 0x3377d1cf, v5
	v_fmac_f32_e32 v13, 0x3f317217, v5
	v_cmp_lt_f32_e64 s[18:19], |v5|, s85
	s_nop 1
	v_cndmask_b32_e64 v5, v5, v13, s[18:19]
	v_cndmask_b32_e32 v13, 0, v202, vcc
	v_sub_f32_e32 v5, v5, v13
	v_cvt_f16_f32_sdwa v5, v5 dst_sel:WORD_1 dst_unused:UNUSED_PAD src0_sel:DWORD
	s_nop 0
	v_or_b32_e32 v13, v5, v9
.LBB0_1255:
	s_or_b64 exec, exec, s[78:79]
	s_and_saveexec_b64 s[78:79], s[14:15]
	s_cbranch_execz .LBB0_1257
	v_or_b32_e32 v14, 3, v4
	v_readlane_b32 s18, v254, 11
	v_ashrrev_i32_e32 v15, 31, v14
	v_readlane_b32 s19, v254, 12
	s_nop 1
	v_lshl_add_u64 v[16:17], v[14:15], 2, s[18:19]
	s_waitcnt vmcnt(0)
	v_mov_b32_e32 v5, v221
	v_lshlrev_b64 v[14:15], 14, v[14:15]
	v_lshl_add_u64 v[14:15], v[2:3], 0, v[14:15]
	s_waitcnt vmcnt(0)
	v_fmamk_f32 v5, v5, 0x3a800000, v201
	v_cmp_gt_f32_e32 vcc, s83, v5
	v_mul_f32_e32 v9, 0x4b800000, v5
	s_nop 0
	v_cndmask_b32_e32 v5, v5, v9, vcc
	v_rsq_f32_e32 v5, v5
	s_nop 0
	v_mul_f32_e32 v9, 0x45800000, v5
	v_cndmask_b32_e32 v5, v5, v9, vcc
	v_add_co_u32_e32 v14, vcc, 0x1000, v14
	s_nop 1
	v_addc_co_u32_e32 v15, vcc, 0, v15, vcc
	v_mov_b64_e32 v[14:15], v[232:233]
	s_waitcnt vmcnt(0)
	v_mul_f32_e32 v9, v14, v5
	v_mul_f32_e32 v9, 0xbfb8aa3b, v9
	v_exp_f32_e32 v9, v9
	v_mul_f32_e32 v5, v15, v5
	v_mul_f32_e32 v5, 0xbfb8aa3b, v5
	v_exp_f32_e32 v5, v5
	v_add_f32_e32 v9, 1.0, v9
	v_rcp_f32_e32 v9, v9
	v_add_f32_e32 v5, 1.0, v5
	v_rcp_f32_e32 v5, v5
	v_fma_f32 v9, v7, v9, v0
	v_cmp_gt_f32_e32 vcc, s83, v9
	v_fma_f32 v5, v6, v5, v1
	s_nop 0
	v_cndmask_b32_e64 v12, 0, 32, vcc
	v_ldexp_f32 v9, v9, v12
	v_log_f32_e32 v9, v9
	s_nop 0
	v_mul_f32_e32 v12, 0x3f317217, v9
	v_fma_f32 v12, v9, s84, -v12
	v_fmac_f32_e32 v12, 0x3377d1cf, v9
	v_fmac_f32_e32 v12, 0x3f317217, v9
	v_cmp_lt_f32_e64 s[18:19], |v9|, s85
	s_nop 1
	v_cndmask_b32_e64 v9, v9, v12, s[18:19]
	v_cndmask_b32_e32 v12, 0, v202, vcc
	v_cmp_gt_f32_e32 vcc, s83, v5
	v_sub_f32_e32 v9, v9, v12
	v_cvt_f16_f32_e32 v9, v9
	v_cndmask_b32_e64 v12, 0, 32, vcc
	v_ldexp_f32 v5, v5, v12
	v_log_f32_e32 v5, v5
	s_nop 0
	v_mul_f32_e32 v12, 0x3f317217, v5
	v_fma_f32 v12, v5, s84, -v12
	v_fmac_f32_e32 v12, 0x3377d1cf, v5
	v_fmac_f32_e32 v12, 0x3f317217, v5
	v_cmp_lt_f32_e64 s[18:19], |v5|, s85
	s_nop 1
	v_cndmask_b32_e64 v5, v5, v12, s[18:19]
	v_cndmask_b32_e32 v12, 0, v202, vcc
	v_sub_f32_e32 v5, v5, v12
	v_cvt_f16_f32_sdwa v5, v5 dst_sel:WORD_1 dst_unused:UNUSED_PAD src0_sel:DWORD
	s_nop 0
	v_or_b32_e32 v12, v5, v9
.LBB0_1257:
	s_or_b64 exec, exec, s[78:79]
	v_mov_b32_e32 v14, 0
	v_mov_b32_e32 v15, 0
	s_and_saveexec_b64 s[78:79], s[14:15]
	s_cbranch_execz .LBB0_1259
	v_or_b32_e32 v16, 4, v4
	v_readlane_b32 s18, v254, 11
	v_ashrrev_i32_e32 v17, 31, v16
	v_readlane_b32 s19, v254, 12
	s_nop 1
	v_lshl_add_u64 v[18:19], v[16:17], 2, s[18:19]
	s_waitcnt vmcnt(0)
	v_mov_b32_e32 v5, v222
	v_lshlrev_b64 v[16:17], 14, v[16:17]
	v_lshl_add_u64 v[16:17], v[2:3], 0, v[16:17]
	s_waitcnt vmcnt(0)
	v_fmamk_f32 v5, v5, 0x3a800000, v201
	v_cmp_gt_f32_e32 vcc, s83, v5
	v_mul_f32_e32 v9, 0x4b800000, v5
	s_nop 0
	v_cndmask_b32_e32 v5, v5, v9, vcc
	v_rsq_f32_e32 v5, v5
	s_nop 0
	v_mul_f32_e32 v9, 0x45800000, v5
	v_cndmask_b32_e32 v5, v5, v9, vcc
	v_add_co_u32_e32 v16, vcc, 0x1000, v16
	s_nop 1
	v_addc_co_u32_e32 v17, vcc, 0, v17, vcc
	v_mov_b64_e32 v[16:17], v[234:235]
	s_waitcnt vmcnt(0)
	v_mul_f32_e32 v9, v16, v5
	v_mul_f32_e32 v9, 0xbfb8aa3b, v9
	v_exp_f32_e32 v9, v9
	v_mul_f32_e32 v5, v17, v5
	v_mul_f32_e32 v5, 0xbfb8aa3b, v5
	v_exp_f32_e32 v5, v5
	v_add_f32_e32 v9, 1.0, v9
	v_rcp_f32_e32 v9, v9
	v_add_f32_e32 v5, 1.0, v5
	v_rcp_f32_e32 v5, v5
	v_fma_f32 v9, v7, v9, v0
	v_cmp_gt_f32_e32 vcc, s83, v9
	v_fma_f32 v5, v6, v5, v1
	s_nop 0
	v_cndmask_b32_e64 v15, 0, 32, vcc
	v_ldexp_f32 v9, v9, v15
	v_log_f32_e32 v9, v9
	s_nop 0
	v_mul_f32_e32 v15, 0x3f317217, v9
	v_fma_f32 v15, v9, s84, -v15
	v_fmac_f32_e32 v15, 0x3377d1cf, v9
	v_fmac_f32_e32 v15, 0x3f317217, v9
	v_cmp_lt_f32_e64 s[18:19], |v9|, s85
	s_nop 1
	v_cndmask_b32_e64 v9, v9, v15, s[18:19]
	v_cndmask_b32_e32 v15, 0, v202, vcc
	v_cmp_gt_f32_e32 vcc, s83, v5
	v_sub_f32_e32 v9, v9, v15
	v_cvt_f16_f32_e32 v9, v9
	v_cndmask_b32_e64 v15, 0, 32, vcc
	v_ldexp_f32 v5, v5, v15
	v_log_f32_e32 v5, v5
	s_nop 0
	v_mul_f32_e32 v15, 0x3f317217, v5
	v_fma_f32 v15, v5, s84, -v15
	v_fmac_f32_e32 v15, 0x3377d1cf, v5
	v_fmac_f32_e32 v15, 0x3f317217, v5
	v_cmp_lt_f32_e64 s[18:19], |v5|, s85
	s_nop 1
	v_cndmask_b32_e64 v5, v5, v15, s[18:19]
	v_cndmask_b32_e32 v15, 0, v202, vcc
	v_sub_f32_e32 v5, v5, v15
	v_cvt_f16_f32_sdwa v5, v5 dst_sel:WORD_1 dst_unused:UNUSED_PAD src0_sel:DWORD
	s_nop 0
	v_or_b32_e32 v15, v5, v9
.LBB0_1259:
	s_or_b64 exec, exec, s[78:79]
	s_and_saveexec_b64 s[78:79], s[14:15]
	s_cbranch_execz .LBB0_1261
	v_or_b32_e32 v16, 5, v4
	v_readlane_b32 s18, v254, 11
	v_ashrrev_i32_e32 v17, 31, v16
	v_readlane_b32 s19, v254, 12
	s_nop 1
	v_lshl_add_u64 v[18:19], v[16:17], 2, s[18:19]
	s_waitcnt vmcnt(0)
	v_mov_b32_e32 v5, v223
	v_lshlrev_b64 v[16:17], 14, v[16:17]
	v_lshl_add_u64 v[16:17], v[2:3], 0, v[16:17]
	s_waitcnt vmcnt(0)
	v_fmamk_f32 v5, v5, 0x3a800000, v201
	v_cmp_gt_f32_e32 vcc, s83, v5
	v_mul_f32_e32 v9, 0x4b800000, v5
	s_nop 0
	v_cndmask_b32_e32 v5, v5, v9, vcc
	v_rsq_f32_e32 v5, v5
	s_nop 0
	v_mul_f32_e32 v9, 0x45800000, v5
	v_cndmask_b32_e32 v5, v5, v9, vcc
	v_add_co_u32_e32 v16, vcc, 0x1000, v16
	s_nop 1
	v_addc_co_u32_e32 v17, vcc, 0, v17, vcc
	v_mov_b64_e32 v[16:17], v[236:237]
	s_waitcnt vmcnt(0)
	v_mul_f32_e32 v9, v16, v5
	v_mul_f32_e32 v9, 0xbfb8aa3b, v9
	v_exp_f32_e32 v9, v9
	v_mul_f32_e32 v5, v17, v5
	v_mul_f32_e32 v5, 0xbfb8aa3b, v5
	v_exp_f32_e32 v5, v5
	v_add_f32_e32 v9, 1.0, v9
	v_rcp_f32_e32 v9, v9
	v_add_f32_e32 v5, 1.0, v5
	v_rcp_f32_e32 v5, v5
	v_fma_f32 v9, v7, v9, v0
	v_cmp_gt_f32_e32 vcc, s83, v9
	v_fma_f32 v5, v6, v5, v1
	s_nop 0
	v_cndmask_b32_e64 v14, 0, 32, vcc
	v_ldexp_f32 v9, v9, v14
	v_log_f32_e32 v9, v9
	s_nop 0
	v_mul_f32_e32 v14, 0x3f317217, v9
	v_fma_f32 v14, v9, s84, -v14
	v_fmac_f32_e32 v14, 0x3377d1cf, v9
	v_fmac_f32_e32 v14, 0x3f317217, v9
	v_cmp_lt_f32_e64 s[18:19], |v9|, s85
	s_nop 1
	v_cndmask_b32_e64 v9, v9, v14, s[18:19]
	v_cndmask_b32_e32 v14, 0, v202, vcc
	v_cmp_gt_f32_e32 vcc, s83, v5
	v_sub_f32_e32 v9, v9, v14
	v_cvt_f16_f32_e32 v9, v9
	v_cndmask_b32_e64 v14, 0, 32, vcc
	v_ldexp_f32 v5, v5, v14
	v_log_f32_e32 v5, v5
	s_nop 0
	v_mul_f32_e32 v14, 0x3f317217, v5
	v_fma_f32 v14, v5, s84, -v14
	v_fmac_f32_e32 v14, 0x3377d1cf, v5
	v_fmac_f32_e32 v14, 0x3f317217, v5
	v_cmp_lt_f32_e64 s[18:19], |v5|, s85
	s_nop 1
	v_cndmask_b32_e64 v5, v5, v14, s[18:19]
	v_cndmask_b32_e32 v14, 0, v202, vcc
	v_sub_f32_e32 v5, v5, v14
	v_cvt_f16_f32_sdwa v5, v5 dst_sel:WORD_1 dst_unused:UNUSED_PAD src0_sel:DWORD
	s_nop 0
	v_or_b32_e32 v14, v5, v9
.LBB0_1261:
	s_or_b64 exec, exec, s[78:79]
	v_mov_b32_e32 v16, 0
	v_mov_b32_e32 v17, 0
	s_and_saveexec_b64 s[78:79], s[14:15]
	s_cbranch_execz .LBB0_1263
	v_or_b32_e32 v18, 6, v4
	v_readlane_b32 s18, v254, 11
	v_ashrrev_i32_e32 v19, 31, v18
	v_readlane_b32 s19, v254, 12
	s_nop 1
	v_lshl_add_u64 v[20:21], v[18:19], 2, s[18:19]
	s_waitcnt vmcnt(0)
	v_mov_b32_e32 v5, v224
	v_lshlrev_b64 v[18:19], 14, v[18:19]
	v_lshl_add_u64 v[18:19], v[2:3], 0, v[18:19]
	s_waitcnt vmcnt(0)
	v_fmamk_f32 v5, v5, 0x3a800000, v201
	v_cmp_gt_f32_e32 vcc, s83, v5
	v_mul_f32_e32 v9, 0x4b800000, v5
	s_nop 0
	v_cndmask_b32_e32 v5, v5, v9, vcc
	v_rsq_f32_e32 v5, v5
	s_nop 0
	v_mul_f32_e32 v9, 0x45800000, v5
	v_cndmask_b32_e32 v5, v5, v9, vcc
	v_add_co_u32_e32 v18, vcc, 0x1000, v18
	s_nop 1
	v_addc_co_u32_e32 v19, vcc, 0, v19, vcc
	v_mov_b64_e32 v[18:19], v[238:239]
	s_waitcnt vmcnt(0)
	v_mul_f32_e32 v9, v18, v5
	v_mul_f32_e32 v9, 0xbfb8aa3b, v9
	v_exp_f32_e32 v9, v9
	v_mul_f32_e32 v5, v19, v5
	v_mul_f32_e32 v5, 0xbfb8aa3b, v5
	v_exp_f32_e32 v5, v5
	v_add_f32_e32 v9, 1.0, v9
	v_rcp_f32_e32 v9, v9
	v_add_f32_e32 v5, 1.0, v5
	v_rcp_f32_e32 v5, v5
	v_fma_f32 v9, v7, v9, v0
	v_cmp_gt_f32_e32 vcc, s83, v9
	v_fma_f32 v5, v6, v5, v1
	s_nop 0
	v_cndmask_b32_e64 v17, 0, 32, vcc
	v_ldexp_f32 v9, v9, v17
	v_log_f32_e32 v9, v9
	s_nop 0
	v_mul_f32_e32 v17, 0x3f317217, v9
	v_fma_f32 v17, v9, s84, -v17
	v_fmac_f32_e32 v17, 0x3377d1cf, v9
	v_fmac_f32_e32 v17, 0x3f317217, v9
	v_cmp_lt_f32_e64 s[18:19], |v9|, s85
	s_nop 1
	v_cndmask_b32_e64 v9, v9, v17, s[18:19]
	v_cndmask_b32_e32 v17, 0, v202, vcc
	v_cmp_gt_f32_e32 vcc, s83, v5
	v_sub_f32_e32 v9, v9, v17
	v_cvt_f16_f32_e32 v9, v9
	v_cndmask_b32_e64 v17, 0, 32, vcc
	v_ldexp_f32 v5, v5, v17
	v_log_f32_e32 v5, v5
	s_nop 0
	v_mul_f32_e32 v17, 0x3f317217, v5
	v_fma_f32 v17, v5, s84, -v17
	v_fmac_f32_e32 v17, 0x3377d1cf, v5
	v_fmac_f32_e32 v17, 0x3f317217, v5
	v_cmp_lt_f32_e64 s[18:19], |v5|, s85
	s_nop 1
	v_cndmask_b32_e64 v5, v5, v17, s[18:19]
	v_cndmask_b32_e32 v17, 0, v202, vcc
	v_sub_f32_e32 v5, v5, v17
	v_cvt_f16_f32_sdwa v5, v5 dst_sel:WORD_1 dst_unused:UNUSED_PAD src0_sel:DWORD
	s_nop 0
	v_or_b32_e32 v17, v5, v9
.LBB0_1263:
	s_or_b64 exec, exec, s[78:79]
	s_and_saveexec_b64 s[18:19], s[14:15]
	s_cbranch_execz .LBB0_1265
	v_or_b32_e32 v4, 7, v4
	v_readlane_b32 s14, v254, 11
	v_ashrrev_i32_e32 v5, 31, v4
	v_readlane_b32 s15, v254, 12
	s_nop 1
	v_lshl_add_u64 v[18:19], v[4:5], 2, s[14:15]
	s_waitcnt vmcnt(0)
	v_mov_b32_e32 v9, v225
	v_lshlrev_b64 v[4:5], 14, v[4:5]
	v_lshl_add_u64 v[2:3], v[2:3], 0, v[4:5]
	v_add_co_u32_e32 v2, vcc, 0x1000, v2
	s_nop 1
	v_addc_co_u32_e32 v3, vcc, 0, v3, vcc
	v_mov_b64_e32 v[2:3], v[240:241]
	s_waitcnt vmcnt(1)
	v_fmamk_f32 v4, v9, 0x3a800000, v201
	v_mul_f32_e32 v5, 0x4b800000, v4
	v_cmp_gt_f32_e32 vcc, s83, v4
	s_nop 1
	v_cndmask_b32_e32 v4, v4, v5, vcc
	v_rsq_f32_e32 v4, v4
	s_nop 0
	v_mul_f32_e32 v5, 0x45800000, v4
	v_cndmask_b32_e32 v4, v4, v5, vcc
	s_waitcnt vmcnt(0)
	v_mul_f32_e32 v2, v2, v4
	v_mul_f32_e32 v3, v3, v4
	v_mul_f32_e32 v2, 0xbfb8aa3b, v2
	v_mul_f32_e32 v3, 0xbfb8aa3b, v3
	v_exp_f32_e32 v2, v2
	v_exp_f32_e32 v3, v3
	v_add_f32_e32 v2, 1.0, v2
	v_add_f32_e32 v3, 1.0, v3
	v_rcp_f32_e32 v2, v2
	v_rcp_f32_e32 v3, v3
	v_fma_f32 v0, v7, v2, v0
	v_fmac_f32_e32 v1, v6, v3
	v_cmp_gt_f32_e32 vcc, s83, v0
	v_cmp_gt_f32_e64 s[14:15], s83, v1
	s_nop 0
	v_cndmask_b32_e64 v2, 0, 32, vcc
	v_cndmask_b32_e64 v3, 0, 32, s[14:15]
	v_ldexp_f32 v0, v0, v2
	v_ldexp_f32 v1, v1, v3
	v_log_f32_e32 v0, v0
	v_log_f32_e32 v1, v1
	v_cndmask_b32_e32 v2, 0, v202, vcc
	v_cndmask_b32_e64 v3, 0, v202, s[14:15]
	v_mul_f32_e32 v4, 0x3f317217, v0
	v_mul_f32_e32 v5, 0x3f317217, v1
	v_fma_f32 v4, v0, s84, -v4
	v_fma_f32 v5, v1, s84, -v5
	v_fmac_f32_e32 v4, 0x3377d1cf, v0
	v_fmac_f32_e32 v5, 0x3377d1cf, v1
	v_fmac_f32_e32 v4, 0x3f317217, v0
	v_cmp_lt_f32_e64 vcc, |v0|, s85
	v_fmac_f32_e32 v5, 0x3f317217, v1
	s_nop 0
	v_cndmask_b32_e32 v0, v0, v4, vcc
	v_cmp_lt_f32_e64 vcc, |v1|, s85
	v_sub_f32_e32 v0, v0, v2
	v_cvt_f16_f32_e32 v0, v0
	v_cndmask_b32_e32 v1, v1, v5, vcc
	v_sub_f32_e32 v1, v1, v3
	v_cvt_f16_f32_sdwa v1, v1 dst_sel:WORD_1 dst_unused:UNUSED_PAD src0_sel:DWORD
	s_nop 0
	v_or_b32_e32 v16, v1, v0
.LBB0_1265:
	s_or_b64 exec, exec, s[18:19]
	v_lshlrev_b32_e32 v0, 3, v67
	v_and_b32_e32 v1, 0x78, v0
	v_ashrrev_i32_e32 v2, 4, v8
	v_cmp_gt_i32_e32 vcc, 16, v2
	v_mov_b32_e32 v0, 0
	v_lshlrev_b32_e32 v64, 2, v1
	v_mov_b32_e32 v4, 0
	v_mov_b32_e32 v5, 0
	v_mov_b32_e32 v6, 0
	v_mov_b32_e32 v7, 0
	s_and_saveexec_b64 s[14:15], vcc
	s_cbranch_execz .LBB0_1267
	v_readlane_b32 s18, v254, 11
	v_ashrrev_i32_e32 v3, 31, v2
	v_readlane_b32 s19, v254, 12
	s_nop 1
	v_lshl_add_u64 v[4:5], v[2:3], 2, s[18:19]
	global_load_dword v1, v[4:5], off
	v_readlane_b32 s18, v254, 14
	v_lshlrev_b64 v[2:3], 14, v[2:3]
	v_readlane_b32 s19, v254, 15

	v_lshl_add_u64 v[2:3], s[18:19], 0, v[2:3]
	s_lshl_b32 s18, s62, 2
	s_mov_b32 s19, s63
	v_lshl_add_u64 v[2:3], v[2:3], 0, s[18:19]
	v_lshl_add_u64 v[6:7], v[2:3], 0, v[64:65]
	v_add_co_u32_e32 v2, vcc, s86, v6
	s_nop 1
	v_addc_co_u32_e32 v3, vcc, 0, v7, vcc
	v_lshl_add_u64 v[6:7], v[6:7], 0, s[64:65]
	global_load_dwordx4 v[2:5], v[2:3], off
	global_load_dwordx4 v[18:21], v[6:7], off offset:16
	s_waitcnt vmcnt(2)
	v_fmamk_f32 v1, v1, 0x3a800000, v201
	v_cmp_gt_f32_e32 vcc, s83, v1
	v_mul_f32_e32 v6, 0x4b800000, v1
	s_nop 0
	v_cndmask_b32_e32 v1, v1, v6, vcc
	v_rsq_f32_e32 v1, v1
	s_nop 0
	v_mul_f32_e32 v6, 0x45800000, v1
	v_cndmask_b32_e32 v6, v1, v6, vcc
	s_waitcnt vmcnt(1)
	v_pk_mul_f32 v[2:3], v[2:3], v[6:7] op_sel_hi:[1,0]
	v_pk_mul_f32 v[22:23], v[4:5], v[6:7] op_sel_hi:[1,0]
	s_waitcnt vmcnt(0)
	v_pk_mul_f32 v[18:19], v[18:19], v[6:7] op_sel_hi:[1,0]
	v_pk_mul_f32 v[20:21], v[6:7], v[20:21] op_sel_hi:[0,1]
	v_cvt_pk_bf16_f32 v4, v2, v3
	v_cvt_pk_bf16_f32 v5, v22, v23
	v_cvt_pk_bf16_f32 v6, v18, v19
	v_cvt_pk_bf16_f32 v7, v20, v21

.LBB0_1410:
	s_waitcnt vmcnt(0)
	v_lshlrev_b32_e32 v0, 16, v4
	v_and_b32_e32 v1, 0xffff0000, v4
	v_lshlrev_b32_e32 v2, 16, v5
	v_and_b32_e32 v3, 0xffff0000, v5
	v_lshlrev_b32_e32 v4, 16, v6
	v_and_b32_e32 v5, 0xffff0000, v6
	v_lshlrev_b32_e32 v6, 16, v7
	v_and_b32_e32 v7, 0xffff0000, v7
	v_lshlrev_b32_e32 v12, 16, v8
	v_and_b32_e32 v13, 0xffff0000, v8
	v_lshlrev_b32_e32 v14, 16, v9
	v_and_b32_e32 v15, 0xffff0000, v9
	v_lshlrev_b32_e32 v8, 16, v10
	v_and_b32_e32 v9, 0xffff0000, v10
	v_lshlrev_b32_e32 v10, 16, v11
	v_and_b32_e32 v11, 0xffff0000, v11
	v_lshlrev_b32_e32 v20, 16, v16
	v_and_b32_e32 v21, 0xffff0000, v16
	v_lshlrev_b32_e32 v22, 16, v17
	v_and_b32_e32 v23, 0xffff0000, v17
	v_lshlrev_b32_e32 v16, 16, v18
	v_and_b32_e32 v17, 0xffff0000, v18
	v_lshlrev_b32_e32 v18, 16, v19
	v_and_b32_e32 v19, 0xffff0000, v19
	v_lshlrev_b32_e32 v28, 16, v24
	v_and_b32_e32 v29, 0xffff0000, v24
	v_lshlrev_b32_e32 v30, 16, v25
	v_and_b32_e32 v31, 0xffff0000, v25
	v_lshlrev_b32_e32 v24, 16, v26
	v_and_b32_e32 v25, 0xffff0000, v26
	v_lshlrev_b32_e32 v26, 16, v27
	s_andn2_b64 vcc, exec, s[14:15]
	v_and_b32_e32 v27, 0xffff0000, v27
	s_cbranch_vccnz .LBB0_1442
	v_and_b32_e32 v32, 0x7e, v34
	v_or_b32_e32 v32, s62, v32
	v_lshlrev_b32_e32 v34, 2, v32
	global_load_dwordx2 v[32:33], v34, s[46:47]
	v_readlane_b32 s18, v254, 14
	v_ashrrev_i32_e32 v36, 6, v97
	v_mov_b32_e32 v35, v85
	v_readlane_b32 s19, v254, 15
	v_mov_b32_e32 v106, 0
	v_mov_b32_e32 v42, 0
	v_cmp_gt_i32_e64 s[14:15], 2, v36
	v_lshlrev_b32_e32 v36, 3, v36
	v_lshl_add_u64 v[34:35], s[18:19], 0, v[34:35]
	v_mov_b32_e32 v107, 0
	s_and_saveexec_b64 s[98:99], s[14:15]
	s_cbranch_execz .Lhgm_hg3
	v_readlane_b32 s100, v254, 11
	v_readlane_b32 s101, v254, 12
	v_mov_b32_e32 v134, v36
	v_ashrrev_i32_e32 v135, 31, v36
	s_nop 0
	v_lshl_add_u64 v[136:137], v[134:135], 2, s[100:101]
	global_load_dwordx4 v[138:141], v[136:137], off
	global_load_dwordx4 v[142:145], v[136:137], off offset:16
	v_lshlrev_b64 v[134:135], 14, v[134:135]
	v_lshl_add_u64 v[134:135], v[34:35], 0, v[134:135]
	s_mov_b64 s[100:101], 0x1000
	v_lshl_add_u64 v[136:137], v[134:135], 0, s[100:101]
	s_mov_b64 s[100:101], 0x4000
	global_load_dwordx2 v[146:147], v[136:137], off
	global_load_dwordx2 v[162:163], v[134:135], off
	v_lshl_add_u64 v[136:137], v[136:137], 0, s[100:101]
	v_lshl_add_u64 v[134:135], v[134:135], 0, s[100:101]
	global_load_dwordx2 v[148:149], v[136:137], off
	global_load_dwordx2 v[164:165], v[134:135], off
	v_lshl_add_u64 v[136:137], v[136:137], 0, s[100:101]
	v_lshl_add_u64 v[134:135], v[134:135], 0, s[100:101]
	global_load_dwordx2 v[150:151], v[136:137], off
	global_load_dwordx2 v[166:167], v[134:135], off
	v_lshl_add_u64 v[136:137], v[136:137], 0, s[100:101]
	v_lshl_add_u64 v[134:135], v[134:135], 0, s[100:101]
	global_load_dwordx2 v[152:153], v[136:137], off
	global_load_dwordx2 v[168:169], v[134:135], off
	v_lshl_add_u64 v[136:137], v[136:137], 0, s[100:101]
	v_lshl_add_u64 v[134:135], v[134:135], 0, s[100:101]
	global_load_dwordx2 v[154:155], v[136:137], off
	global_load_dwordx2 v[170:171], v[134:135], off
	v_lshl_add_u64 v[136:137], v[136:137], 0, s[100:101]
	v_lshl_add_u64 v[134:135], v[134:135], 0, s[100:101]
	global_load_dwordx2 v[156:157], v[136:137], off
	global_load_dwordx2 v[172:173], v[134:135], off
	v_lshl_add_u64 v[136:137], v[136:137], 0, s[100:101]
	v_lshl_add_u64 v[134:135], v[134:135], 0, s[100:101]
	global_load_dwordx2 v[158:159], v[136:137], off
	global_load_dwordx2 v[174:175], v[134:135], off
	v_lshl_add_u64 v[136:137], v[136:137], 0, s[100:101]
	v_lshl_add_u64 v[134:135], v[134:135], 0, s[100:101]
	global_load_dwordx2 v[160:161], v[136:137], off
	global_load_dwordx2 v[176:177], v[134:135], off
.Lhgm_hg3:
	s_or_b64 exec, exec, s[98:99]
	s_waitcnt vmcnt(0)
	v_sub_f32_e32 v38, 1.0, v32
	v_sub_f32_e32 v39, 1.0, v33
	s_and_saveexec_b64 s[78:79], s[14:15]
	s_cbranch_execz .LBB0_1413
	v_readlane_b32 s18, v254, 11
	v_ashrrev_i32_e32 v37, 31, v36
	v_readlane_b32 s19, v254, 12
	s_nop 1
	v_lshl_add_u64 v[40:41], v[36:37], 2, s[18:19]
	s_waitcnt vmcnt(0)
	v_mov_b32_e32 v44, v138
	v_lshlrev_b64 v[40:41], 14, v[36:37]
	v_lshl_add_u64 v[40:41], v[34:35], 0, v[40:41]
	v_add_co_u32_e32 v42, vcc, 0x1000, v40
	s_waitcnt vmcnt(0)
	v_fmamk_f32 v37, v44, 0x3a800000, v86
	v_addc_co_u32_e32 v43, vcc, 0, v41, vcc
	v_mov_b64_e32 v[42:43], v[146:147]
	s_nop 0
	v_mov_b64_e32 v[40:41], v[162:163]
	v_mul_f32_e32 v44, 0x4b800000, v37
	v_cmp_gt_f32_e32 vcc, s97, v37
	s_nop 1
	v_cndmask_b32_e32 v37, v37, v44, vcc
	v_rsq_f32_e32 v37, v37
	s_nop 0
	v_mul_f32_e32 v44, 0x45800000, v37
	v_cndmask_b32_e32 v44, v37, v44, vcc
	s_waitcnt vmcnt(1)
	v_mul_f32_e32 v37, v42, v44
	v_mul_f32_e32 v42, v43, v44
	v_mul_f32_e32 v37, 0xbfb8aa3b, v37
	v_mul_f32_e32 v42, 0xbfb8aa3b, v42
	v_exp_f32_e32 v37, v37
	v_exp_f32_e32 v42, v42
	s_waitcnt vmcnt(0)
	v_pk_mul_f32 v[40:41], v[40:41], v[44:45] op_sel_hi:[1,0]
	v_add_f32_e32 v37, 1.0, v37
	v_mul_f32_e32 v43, 0xbfb8aa3b, v40
	v_mul_f32_e32 v44, 0xbfb8aa3b, v41
	v_exp_f32_e32 v43, v43
	v_exp_f32_e32 v44, v44
	v_add_f32_e32 v42, 1.0, v42
	v_rcp_f32_e32 v37, v37
	v_rcp_f32_e32 v45, v42
	v_add_f32_e32 v43, 1.0, v43
	v_add_f32_e32 v44, 1.0, v44
	v_fma_f32 v37, v38, v37, v32
	v_rcp_f32_e32 v42, v43
	v_rcp_f32_e32 v43, v44
	v_fma_f32 v44, v39, v45, v33
	v_cmp_gt_f32_e32 vcc, s97, v37
	v_cmp_gt_f32_e64 s[18:19], s97, v44
	v_pk_mul_f32 v[40:41], v[40:41], v[42:43]
	v_cndmask_b32_e64 v45, 0, 32, vcc
	v_cndmask_b32_e64 v46, 0, 32, s[18:19]
	v_ldexp_f32 v37, v37, v45
	v_ldexp_f32 v44, v44, v46
	v_log_f32_e32 v37, v37
	v_log_f32_e32 v44, v44
	v_cndmask_b32_e32 v45, 0, v108, vcc
	v_cndmask_b32_e64 v46, 0, v108, s[18:19]
	v_mul_f32_e32 v47, 0x3f317217, v37
	v_mul_f32_e32 v48, 0x3f317217, v44
	v_fma_f32 v47, v37, s56, -v47
	v_fma_f32 v48, v44, s56, -v48
	v_fmac_f32_e32 v47, 0x3377d1cf, v37
	v_fmac_f32_e32 v48, 0x3377d1cf, v44
	v_fmac_f32_e32 v47, 0x3f317217, v37
	v_cmp_lt_f32_e64 vcc, |v37|, s57
	v_fmac_f32_e32 v48, 0x3f317217, v44
	v_cvt_pk_bf16_f32 v107, v40, v41
	v_cndmask_b32_e32 v37, v37, v47, vcc
	v_cmp_lt_f32_e64 vcc, |v44|, s57
	v_sub_f32_e32 v37, v37, v45
	v_cvt_f16_f32_e32 v37, v37
	v_cndmask_b32_e32 v44, v44, v48, vcc
	v_sub_f32_e32 v44, v44, v46
	v_cvt_f16_f32_sdwa v44, v44 dst_sel:WORD_1 dst_unused:UNUSED_PAD src0_sel:DWORD
	s_nop 0
	v_or_b32_e32 v42, v44, v37
.LBB0_1413:
	s_or_b64 exec, exec, s[78:79]
	v_mov_b32_e32 v43, 0
	s_and_saveexec_b64 s[78:79], s[14:15]
	s_cbranch_execz .LBB0_1415
	v_or_b32_e32 v40, 1, v36
	v_readlane_b32 s18, v254, 11
	v_ashrrev_i32_e32 v41, 31, v40
	v_readlane_b32 s19, v254, 12
	s_nop 1
	v_lshl_add_u64 v[44:45], v[40:41], 2, s[18:19]
	s_waitcnt vmcnt(0)
	v_mov_b32_e32 v37, v139
	v_lshlrev_b64 v[40:41], 14, v[40:41]
	v_lshl_add_u64 v[40:41], v[34:35], 0, v[40:41]
	v_add_co_u32_e32 v44, vcc, 0x1000, v40
	s_waitcnt vmcnt(0)
	v_fmamk_f32 v37, v37, 0x3a800000, v86
	v_addc_co_u32_e32 v45, vcc, 0, v41, vcc
	v_mov_b64_e32 v[44:45], v[148:149]
	s_nop 0
	v_mov_b64_e32 v[40:41], v[164:165]
	v_mul_f32_e32 v43, 0x4b800000, v37
	v_cmp_gt_f32_e32 vcc, s97, v37
	s_nop 1
	v_cndmask_b32_e32 v37, v37, v43, vcc
	v_rsq_f32_e32 v37, v37
	s_nop 0
	v_mul_f32_e32 v43, 0x45800000, v37
	v_cndmask_b32_e32 v46, v37, v43, vcc
	s_waitcnt vmcnt(1)
	v_mul_f32_e32 v37, v44, v46
	v_mul_f32_e32 v43, v45, v46
	v_mul_f32_e32 v37, 0xbfb8aa3b, v37
	v_mul_f32_e32 v43, 0xbfb8aa3b, v43
	v_exp_f32_e32 v37, v37
	v_exp_f32_e32 v43, v43
	s_waitcnt vmcnt(0)
	v_pk_mul_f32 v[40:41], v[40:41], v[46:47] op_sel_hi:[1,0]
	v_add_f32_e32 v37, 1.0, v37
	v_add_f32_e32 v43, 1.0, v43
	v_rcp_f32_e32 v37, v37
	v_rcp_f32_e32 v43, v43
	v_mul_f32_e32 v44, 0xbfb8aa3b, v40
	v_mul_f32_e32 v45, 0xbfb8aa3b, v41
	v_fma_f32 v37, v38, v37, v32
	v_fma_f32 v43, v39, v43, v33
	v_cmp_gt_f32_e32 vcc, s97, v37
	v_cmp_gt_f32_e64 s[18:19], s97, v43
	v_exp_f32_e32 v44, v44
	v_cndmask_b32_e64 v46, 0, 32, vcc
	v_cndmask_b32_e64 v47, 0, 32, s[18:19]
	v_ldexp_f32 v37, v37, v46
	v_ldexp_f32 v43, v43, v47
	v_log_f32_e32 v37, v37
	v_log_f32_e32 v43, v43
	v_exp_f32_e32 v45, v45
	v_cndmask_b32_e32 v46, 0, v108, vcc
	v_mul_f32_e32 v48, 0x3f317217, v37
	v_mul_f32_e32 v49, 0x3f317217, v43
	v_fma_f32 v48, v37, s56, -v48
	v_fma_f32 v49, v43, s56, -v49
	v_fmac_f32_e32 v48, 0x3377d1cf, v37
	v_fmac_f32_e32 v49, 0x3377d1cf, v43
	v_fmac_f32_e32 v48, 0x3f317217, v37
	v_cmp_lt_f32_e64 vcc, |v37|, s57
	v_fmac_f32_e32 v49, 0x3f317217, v43
	v_add_f32_e32 v44, 1.0, v44
	v_cndmask_b32_e32 v37, v37, v48, vcc
	v_cmp_lt_f32_e64 vcc, |v43|, s57
	v_add_f32_e32 v45, 1.0, v45
	v_cndmask_b32_e64 v47, 0, v108, s[18:19]
	v_cndmask_b32_e32 v43, v43, v49, vcc
	v_rcp_f32_e32 v44, v44
	v_rcp_f32_e32 v45, v45
	v_sub_f32_e32 v37, v37, v46
	v_sub_f32_e32 v43, v43, v47
	v_cvt_f16_f32_e32 v37, v37
	v_cvt_f16_f32_sdwa v43, v43 dst_sel:WORD_1 dst_unused:UNUSED_PAD src0_sel:DWORD
	v_pk_mul_f32 v[40:41], v[40:41], v[44:45]
	v_or_b32_e32 v43, v43, v37
	v_cvt_pk_bf16_f32 v106, v40, v41
.LBB0_1415:
	s_or_b64 exec, exec, s[78:79]
	v_mov_b32_e32 v110, 0
	v_mov_b32_e32 v109, 0
	v_mov_b32_e32 v44, 0
	s_and_saveexec_b64 s[78:79], s[14:15]
	s_cbranch_execz .LBB0_1417
	v_or_b32_e32 v40, 2, v36
	v_readlane_b32 s18, v254, 11
	v_ashrrev_i32_e32 v41, 31, v40
	v_readlane_b32 s19, v254, 12
	s_nop 1
	v_lshl_add_u64 v[44:45], v[40:41], 2, s[18:19]
	s_waitcnt vmcnt(0)
	v_mov_b32_e32 v37, v140
	v_lshlrev_b64 v[40:41], 14, v[40:41]
	v_lshl_add_u64 v[40:41], v[34:35], 0, v[40:41]
	v_add_co_u32_e32 v44, vcc, 0x1000, v40
	s_waitcnt vmcnt(0)
	v_fmamk_f32 v37, v37, 0x3a800000, v86
	v_addc_co_u32_e32 v45, vcc, 0, v41, vcc
	v_mov_b64_e32 v[44:45], v[150:151]
	s_nop 0
	v_mov_b64_e32 v[40:41], v[166:167]
	v_mul_f32_e32 v46, 0x4b800000, v37
	v_cmp_gt_f32_e32 vcc, s97, v37
	s_nop 1
	v_cndmask_b32_e32 v37, v37, v46, vcc
	v_rsq_f32_e32 v37, v37
	s_nop 0
	v_mul_f32_e32 v46, 0x45800000, v37
	v_cndmask_b32_e32 v46, v37, v46, vcc
	s_waitcnt vmcnt(1)
	v_mul_f32_e32 v37, v44, v46
	v_mul_f32_e32 v44, v45, v46
	v_mul_f32_e32 v37, 0xbfb8aa3b, v37
	v_mul_f32_e32 v44, 0xbfb8aa3b, v44
	v_exp_f32_e32 v37, v37
	v_exp_f32_e32 v44, v44
	s_waitcnt vmcnt(0)
	v_pk_mul_f32 v[40:41], v[40:41], v[46:47] op_sel_hi:[1,0]
	v_add_f32_e32 v37, 1.0, v37
	v_mul_f32_e32 v45, 0xbfb8aa3b, v40
	v_mul_f32_e32 v46, 0xbfb8aa3b, v41
	v_exp_f32_e32 v45, v45
	v_exp_f32_e32 v46, v46
	v_add_f32_e32 v44, 1.0, v44
	v_rcp_f32_e32 v37, v37
	v_rcp_f32_e32 v47, v44
	v_add_f32_e32 v45, 1.0, v45
	v_add_f32_e32 v46, 1.0, v46
	v_fma_f32 v37, v38, v37, v32
	v_rcp_f32_e32 v44, v45
	v_rcp_f32_e32 v45, v46
	v_fma_f32 v46, v39, v47, v33
	v_cmp_gt_f32_e32 vcc, s97, v37
	v_cmp_gt_f32_e64 s[18:19], s97, v46
	v_pk_mul_f32 v[40:41], v[40:41], v[44:45]
	v_cndmask_b32_e64 v47, 0, 32, vcc
	v_cndmask_b32_e64 v48, 0, 32, s[18:19]
	v_ldexp_f32 v37, v37, v47
	v_ldexp_f32 v46, v46, v48
	v_log_f32_e32 v37, v37
	v_log_f32_e32 v46, v46
	v_cndmask_b32_e32 v47, 0, v108, vcc
	v_cndmask_b32_e64 v48, 0, v108, s[18:19]
	v_mul_f32_e32 v49, 0x3f317217, v37
	v_mul_f32_e32 v50, 0x3f317217, v46
	v_fma_f32 v49, v37, s56, -v49
	v_fma_f32 v50, v46, s56, -v50
	v_fmac_f32_e32 v49, 0x3377d1cf, v37
	v_fmac_f32_e32 v50, 0x3377d1cf, v46
	v_fmac_f32_e32 v49, 0x3f317217, v37
	v_cmp_lt_f32_e64 vcc, |v37|, s57
	v_fmac_f32_e32 v50, 0x3f317217, v46
	v_cvt_pk_bf16_f32 v109, v40, v41
	v_cndmask_b32_e32 v37, v37, v49, vcc
	v_cmp_lt_f32_e64 vcc, |v46|, s57
	v_sub_f32_e32 v37, v37, v47
	v_cvt_f16_f32_e32 v37, v37
	v_cndmask_b32_e32 v46, v46, v50, vcc
	v_sub_f32_e32 v46, v46, v48
	v_cvt_f16_f32_sdwa v46, v46 dst_sel:WORD_1 dst_unused:UNUSED_PAD src0_sel:DWORD
	s_nop 0
	v_or_b32_e32 v44, v46, v37
.LBB0_1417:
	s_or_b64 exec, exec, s[78:79]
	v_mov_b32_e32 v45, 0
	s_and_saveexec_b64 s[78:79], s[14:15]
	s_cbranch_execz .LBB0_1419
	v_or_b32_e32 v40, 3, v36
	v_readlane_b32 s18, v254, 11
	v_ashrrev_i32_e32 v41, 31, v40
	v_readlane_b32 s19, v254, 12
	s_nop 1
	v_lshl_add_u64 v[46:47], v[40:41], 2, s[18:19]
	s_waitcnt vmcnt(0)
	v_mov_b32_e32 v37, v141
	v_lshlrev_b64 v[40:41], 14, v[40:41]
	v_lshl_add_u64 v[40:41], v[34:35], 0, v[40:41]
	v_add_co_u32_e32 v46, vcc, 0x1000, v40
	s_waitcnt vmcnt(0)
	v_fmamk_f32 v37, v37, 0x3a800000, v86
	v_addc_co_u32_e32 v47, vcc, 0, v41, vcc
	v_mov_b64_e32 v[46:47], v[152:153]
	s_nop 0
	v_mov_b64_e32 v[40:41], v[168:169]
	v_mul_f32_e32 v45, 0x4b800000, v37
	v_cmp_gt_f32_e32 vcc, s97, v37
	s_nop 1
	v_cndmask_b32_e32 v37, v37, v45, vcc
	v_rsq_f32_e32 v37, v37
	s_nop 0
	v_mul_f32_e32 v45, 0x45800000, v37
	v_cndmask_b32_e32 v48, v37, v45, vcc
	s_waitcnt vmcnt(1)
	v_mul_f32_e32 v37, v46, v48
	v_mul_f32_e32 v45, v47, v48
	v_mul_f32_e32 v37, 0xbfb8aa3b, v37
	v_mul_f32_e32 v45, 0xbfb8aa3b, v45
	v_exp_f32_e32 v37, v37
	v_exp_f32_e32 v45, v45
	s_waitcnt vmcnt(0)
	v_pk_mul_f32 v[40:41], v[40:41], v[48:49] op_sel_hi:[1,0]
	v_add_f32_e32 v37, 1.0, v37
	v_add_f32_e32 v45, 1.0, v45
	v_rcp_f32_e32 v37, v37
	v_rcp_f32_e32 v45, v45
	v_mul_f32_e32 v46, 0xbfb8aa3b, v40
	v_mul_f32_e32 v47, 0xbfb8aa3b, v41
	v_fma_f32 v37, v38, v37, v32
	v_fma_f32 v45, v39, v45, v33
	v_cmp_gt_f32_e32 vcc, s97, v37
	v_cmp_gt_f32_e64 s[18:19], s97, v45
	v_exp_f32_e32 v46, v46
	v_cndmask_b32_e64 v48, 0, 32, vcc
	v_cndmask_b32_e64 v49, 0, 32, s[18:19]
	v_ldexp_f32 v37, v37, v48
	v_ldexp_f32 v45, v45, v49
	v_log_f32_e32 v37, v37
	v_log_f32_e32 v45, v45
	v_exp_f32_e32 v47, v47
	v_cndmask_b32_e32 v48, 0, v108, vcc
	v_mul_f32_e32 v50, 0x3f317217, v37
	v_mul_f32_e32 v51, 0x3f317217, v45
	v_fma_f32 v50, v37, s56, -v50
	v_fma_f32 v51, v45, s56, -v51
	v_fmac_f32_e32 v50, 0x3377d1cf, v37
	v_fmac_f32_e32 v51, 0x3377d1cf, v45
	v_fmac_f32_e32 v50, 0x3f317217, v37
	v_cmp_lt_f32_e64 vcc, |v37|, s57
	v_fmac_f32_e32 v51, 0x3f317217, v45
	v_add_f32_e32 v46, 1.0, v46
	v_cndmask_b32_e32 v37, v37, v50, vcc
	v_cmp_lt_f32_e64 vcc, |v45|, s57
	v_add_f32_e32 v47, 1.0, v47
	v_cndmask_b32_e64 v49, 0, v108, s[18:19]
	v_cndmask_b32_e32 v45, v45, v51, vcc
	v_rcp_f32_e32 v46, v46
	v_rcp_f32_e32 v47, v47
	v_sub_f32_e32 v37, v37, v48
	v_sub_f32_e32 v45, v45, v49
	v_cvt_f16_f32_e32 v37, v37
	v_cvt_f16_f32_sdwa v45, v45 dst_sel:WORD_1 dst_unused:UNUSED_PAD src0_sel:DWORD
	v_pk_mul_f32 v[40:41], v[40:41], v[46:47]
	v_or_b32_e32 v45, v45, v37
	v_cvt_pk_bf16_f32 v110, v40, v41
.LBB0_1419:
	s_or_b64 exec, exec, s[78:79]
	v_mov_b32_e32 v112, 0
	v_mov_b32_e32 v111, 0
	v_mov_b32_e32 v46, 0
	s_and_saveexec_b64 s[78:79], s[14:15]
	s_cbranch_execz .LBB0_1421
	v_or_b32_e32 v40, 4, v36
	v_readlane_b32 s18, v254, 11
	v_ashrrev_i32_e32 v41, 31, v40
	v_readlane_b32 s19, v254, 12
	s_nop 1
	v_lshl_add_u64 v[46:47], v[40:41], 2, s[18:19]
	s_waitcnt vmcnt(0)
	v_mov_b32_e32 v37, v142
	v_lshlrev_b64 v[40:41], 14, v[40:41]
	v_lshl_add_u64 v[40:41], v[34:35], 0, v[40:41]
	v_add_co_u32_e32 v46, vcc, 0x1000, v40
	s_waitcnt vmcnt(0)
	v_fmamk_f32 v37, v37, 0x3a800000, v86
	v_addc_co_u32_e32 v47, vcc, 0, v41, vcc
	v_mov_b64_e32 v[46:47], v[154:155]
	s_nop 0
	v_mov_b64_e32 v[40:41], v[170:171]
	v_mul_f32_e32 v48, 0x4b800000, v37
	v_cmp_gt_f32_e32 vcc, s97, v37
	s_nop 1
	v_cndmask_b32_e32 v37, v37, v48, vcc
	v_rsq_f32_e32 v37, v37
	s_nop 0
	v_mul_f32_e32 v48, 0x45800000, v37
	v_cndmask_b32_e32 v48, v37, v48, vcc
	s_waitcnt vmcnt(1)
	v_mul_f32_e32 v37, v46, v48
	v_mul_f32_e32 v46, v47, v48
	v_mul_f32_e32 v37, 0xbfb8aa3b, v37
	v_mul_f32_e32 v46, 0xbfb8aa3b, v46
	v_exp_f32_e32 v37, v37
	v_exp_f32_e32 v46, v46
	s_waitcnt vmcnt(0)
	v_pk_mul_f32 v[40:41], v[40:41], v[48:49] op_sel_hi:[1,0]
	v_add_f32_e32 v37, 1.0, v37
	v_mul_f32_e32 v47, 0xbfb8aa3b, v40
	v_mul_f32_e32 v48, 0xbfb8aa3b, v41
	v_exp_f32_e32 v47, v47
	v_exp_f32_e32 v48, v48
	v_add_f32_e32 v46, 1.0, v46
	v_rcp_f32_e32 v37, v37
	v_rcp_f32_e32 v49, v46
	v_add_f32_e32 v47, 1.0, v47
	v_add_f32_e32 v48, 1.0, v48
	v_fma_f32 v37, v38, v37, v32
	v_rcp_f32_e32 v46, v47
	v_rcp_f32_e32 v47, v48
	v_fma_f32 v48, v39, v49, v33
	v_cmp_gt_f32_e32 vcc, s97, v37
	v_cmp_gt_f32_e64 s[18:19], s97, v48
	v_pk_mul_f32 v[40:41], v[40:41], v[46:47]
	v_cndmask_b32_e64 v49, 0, 32, vcc
	v_cndmask_b32_e64 v50, 0, 32, s[18:19]
	v_ldexp_f32 v37, v37, v49
	v_ldexp_f32 v48, v48, v50
	v_log_f32_e32 v37, v37
	v_log_f32_e32 v48, v48
	v_cndmask_b32_e32 v49, 0, v108, vcc
	v_cndmask_b32_e64 v50, 0, v108, s[18:19]
	v_mul_f32_e32 v51, 0x3f317217, v37
	v_mul_f32_e32 v52, 0x3f317217, v48
	v_fma_f32 v51, v37, s56, -v51
	v_fma_f32 v52, v48, s56, -v52
	v_fmac_f32_e32 v51, 0x3377d1cf, v37
	v_fmac_f32_e32 v52, 0x3377d1cf, v48
	v_fmac_f32_e32 v51, 0x3f317217, v37
	v_cmp_lt_f32_e64 vcc, |v37|, s57
	v_fmac_f32_e32 v52, 0x3f317217, v48
	v_cvt_pk_bf16_f32 v111, v40, v41
	v_cndmask_b32_e32 v37, v37, v51, vcc
	v_cmp_lt_f32_e64 vcc, |v48|, s57
	v_sub_f32_e32 v37, v37, v49
	v_cvt_f16_f32_e32 v37, v37
	v_cndmask_b32_e32 v48, v48, v52, vcc
	v_sub_f32_e32 v48, v48, v50
	v_cvt_f16_f32_sdwa v48, v48 dst_sel:WORD_1 dst_unused:UNUSED_PAD src0_sel:DWORD
	s_nop 0
	v_or_b32_e32 v46, v48, v37
.LBB0_1421:
	s_or_b64 exec, exec, s[78:79]
	v_mov_b32_e32 v47, 0
	s_and_saveexec_b64 s[78:79], s[14:15]
	s_cbranch_execz .LBB0_1423
	v_or_b32_e32 v40, 5, v36
	v_readlane_b32 s18, v254, 11
	v_ashrrev_i32_e32 v41, 31, v40
	v_readlane_b32 s19, v254, 12
	s_nop 1
	v_lshl_add_u64 v[48:49], v[40:41], 2, s[18:19]
	s_waitcnt vmcnt(0)
	v_mov_b32_e32 v37, v143
	v_lshlrev_b64 v[40:41], 14, v[40:41]
	v_lshl_add_u64 v[40:41], v[34:35], 0, v[40:41]
	v_add_co_u32_e32 v48, vcc, 0x1000, v40
	s_waitcnt vmcnt(0)
	v_fmamk_f32 v37, v37, 0x3a800000, v86
	v_addc_co_u32_e32 v49, vcc, 0, v41, vcc
	v_mov_b64_e32 v[48:49], v[156:157]
	s_nop 0
	v_mov_b64_e32 v[40:41], v[172:173]
	v_mul_f32_e32 v47, 0x4b800000, v37
	v_cmp_gt_f32_e32 vcc, s97, v37
	s_nop 1
	v_cndmask_b32_e32 v37, v37, v47, vcc
	v_rsq_f32_e32 v37, v37
	s_nop 0
	v_mul_f32_e32 v47, 0x45800000, v37
	v_cndmask_b32_e32 v50, v37, v47, vcc
	s_waitcnt vmcnt(1)
	v_mul_f32_e32 v37, v48, v50
	v_mul_f32_e32 v47, v49, v50
	v_mul_f32_e32 v37, 0xbfb8aa3b, v37
	v_mul_f32_e32 v47, 0xbfb8aa3b, v47
	v_exp_f32_e32 v37, v37
	v_exp_f32_e32 v47, v47
	s_waitcnt vmcnt(0)
	v_pk_mul_f32 v[40:41], v[40:41], v[50:51] op_sel_hi:[1,0]
	v_add_f32_e32 v37, 1.0, v37
	v_add_f32_e32 v47, 1.0, v47
	v_rcp_f32_e32 v37, v37
	v_rcp_f32_e32 v47, v47
	v_mul_f32_e32 v48, 0xbfb8aa3b, v40
	v_mul_f32_e32 v49, 0xbfb8aa3b, v41
	v_fma_f32 v37, v38, v37, v32
	v_fma_f32 v47, v39, v47, v33
	v_cmp_gt_f32_e32 vcc, s97, v37
	v_cmp_gt_f32_e64 s[18:19], s97, v47
	v_exp_f32_e32 v48, v48
	v_cndmask_b32_e64 v50, 0, 32, vcc
	v_cndmask_b32_e64 v51, 0, 32, s[18:19]
	v_ldexp_f32 v37, v37, v50
	v_ldexp_f32 v47, v47, v51
	v_log_f32_e32 v37, v37
	v_log_f32_e32 v47, v47
	v_exp_f32_e32 v49, v49
	v_cndmask_b32_e32 v50, 0, v108, vcc
	v_mul_f32_e32 v52, 0x3f317217, v37
	v_mul_f32_e32 v53, 0x3f317217, v47
	v_fma_f32 v52, v37, s56, -v52
	v_fma_f32 v53, v47, s56, -v53
	v_fmac_f32_e32 v52, 0x3377d1cf, v37
	v_fmac_f32_e32 v53, 0x3377d1cf, v47
	v_fmac_f32_e32 v52, 0x3f317217, v37
	v_cmp_lt_f32_e64 vcc, |v37|, s57
	v_fmac_f32_e32 v53, 0x3f317217, v47
	v_add_f32_e32 v48, 1.0, v48
	v_cndmask_b32_e32 v37, v37, v52, vcc
	v_cmp_lt_f32_e64 vcc, |v47|, s57
	v_add_f32_e32 v49, 1.0, v49
	v_cndmask_b32_e64 v51, 0, v108, s[18:19]
	v_cndmask_b32_e32 v47, v47, v53, vcc
	v_rcp_f32_e32 v48, v48
	v_rcp_f32_e32 v49, v49
	v_sub_f32_e32 v37, v37, v50
	v_sub_f32_e32 v47, v47, v51
	v_cvt_f16_f32_e32 v37, v37
	v_cvt_f16_f32_sdwa v47, v47 dst_sel:WORD_1 dst_unused:UNUSED_PAD src0_sel:DWORD
	v_pk_mul_f32 v[40:41], v[40:41], v[48:49]
	v_or_b32_e32 v47, v47, v37
	v_cvt_pk_bf16_f32 v112, v40, v41
.LBB0_1423:
	s_or_b64 exec, exec, s[78:79]
	v_mov_b32_e32 v114, 0
	v_mov_b32_e32 v113, 0
	v_mov_b32_e32 v48, 0
	s_and_saveexec_b64 s[78:79], s[14:15]
	s_cbranch_execz .LBB0_1425
	v_or_b32_e32 v40, 6, v36
	v_readlane_b32 s18, v254, 11
	v_ashrrev_i32_e32 v41, 31, v40
	v_readlane_b32 s19, v254, 12
	s_nop 1
	v_lshl_add_u64 v[48:49], v[40:41], 2, s[18:19]
	s_waitcnt vmcnt(0)
	v_mov_b32_e32 v37, v144
	v_lshlrev_b64 v[40:41], 14, v[40:41]
	v_lshl_add_u64 v[40:41], v[34:35], 0, v[40:41]
	v_add_co_u32_e32 v48, vcc, 0x1000, v40
	s_waitcnt vmcnt(0)
	v_fmamk_f32 v37, v37, 0x3a800000, v86
	v_addc_co_u32_e32 v49, vcc, 0, v41, vcc
	v_mov_b64_e32 v[48:49], v[158:159]
	s_nop 0
	v_mov_b64_e32 v[40:41], v[174:175]
	v_mul_f32_e32 v50, 0x4b800000, v37
	v_cmp_gt_f32_e32 vcc, s97, v37
	s_nop 1
	v_cndmask_b32_e32 v37, v37, v50, vcc
	v_rsq_f32_e32 v37, v37
	s_nop 0
	v_mul_f32_e32 v50, 0x45800000, v37
	v_cndmask_b32_e32 v50, v37, v50, vcc
	s_waitcnt vmcnt(1)
	v_mul_f32_e32 v37, v48, v50
	v_mul_f32_e32 v48, v49, v50
	v_mul_f32_e32 v37, 0xbfb8aa3b, v37
	v_mul_f32_e32 v48, 0xbfb8aa3b, v48
	v_exp_f32_e32 v37, v37
	v_exp_f32_e32 v48, v48
	s_waitcnt vmcnt(0)
	v_pk_mul_f32 v[40:41], v[40:41], v[50:51] op_sel_hi:[1,0]
	v_add_f32_e32 v37, 1.0, v37
	v_mul_f32_e32 v49, 0xbfb8aa3b, v40
	v_mul_f32_e32 v50, 0xbfb8aa3b, v41
	v_exp_f32_e32 v49, v49
	v_exp_f32_e32 v50, v50
	v_add_f32_e32 v48, 1.0, v48
	v_rcp_f32_e32 v37, v37
	v_rcp_f32_e32 v51, v48
	v_add_f32_e32 v49, 1.0, v49
	v_add_f32_e32 v50, 1.0, v50
	v_fma_f32 v37, v38, v37, v32
	v_rcp_f32_e32 v48, v49
	v_rcp_f32_e32 v49, v50
	v_fma_f32 v50, v39, v51, v33
	v_cmp_gt_f32_e32 vcc, s97, v37
	v_cmp_gt_f32_e64 s[18:19], s97, v50
	v_pk_mul_f32 v[40:41], v[40:41], v[48:49]
	v_cndmask_b32_e64 v51, 0, 32, vcc
	v_cndmask_b32_e64 v52, 0, 32, s[18:19]
	v_ldexp_f32 v37, v37, v51
	v_ldexp_f32 v50, v50, v52
	v_log_f32_e32 v37, v37
	v_log_f32_e32 v50, v50
	v_cndmask_b32_e32 v51, 0, v108, vcc
	v_cndmask_b32_e64 v52, 0, v108, s[18:19]
	v_mul_f32_e32 v53, 0x3f317217, v37
	v_mul_f32_e32 v54, 0x3f317217, v50
	v_fma_f32 v53, v37, s56, -v53
	v_fma_f32 v54, v50, s56, -v54
	v_fmac_f32_e32 v53, 0x3377d1cf, v37
	v_fmac_f32_e32 v54, 0x3377d1cf, v50
	v_fmac_f32_e32 v53, 0x3f317217, v37
	v_cmp_lt_f32_e64 vcc, |v37|, s57
	v_fmac_f32_e32 v54, 0x3f317217, v50
	v_cvt_pk_bf16_f32 v113, v40, v41
	v_cndmask_b32_e32 v37, v37, v53, vcc
	v_cmp_lt_f32_e64 vcc, |v50|, s57
	v_sub_f32_e32 v37, v37, v51
	v_cvt_f16_f32_e32 v37, v37
	v_cndmask_b32_e32 v50, v50, v54, vcc
	v_sub_f32_e32 v50, v50, v52
	v_cvt_f16_f32_sdwa v50, v50 dst_sel:WORD_1 dst_unused:UNUSED_PAD src0_sel:DWORD
	s_nop 0
	v_or_b32_e32 v48, v50, v37
.LBB0_1425:
	s_or_b64 exec, exec, s[78:79]
	v_mov_b32_e32 v49, 0
	s_and_saveexec_b64 s[18:19], s[14:15]
	s_cbranch_execz .LBB0_1427
	v_or_b32_e32 v36, 7, v36
	v_readlane_b32 s14, v254, 11
	v_ashrrev_i32_e32 v37, 31, v36
	v_readlane_b32 s15, v254, 12
	s_nop 1
	v_lshl_add_u64 v[40:41], v[36:37], 2, s[14:15]
	s_waitcnt vmcnt(0)
	v_mov_b32_e32 v40, v145
	v_lshlrev_b64 v[36:37], 14, v[36:37]
	v_lshl_add_u64 v[34:35], v[34:35], 0, v[36:37]
	v_add_co_u32_e32 v36, vcc, 0x1000, v34
	s_waitcnt vmcnt(0)
	v_fmamk_f32 v40, v40, 0x3a800000, v86
	v_addc_co_u32_e32 v37, vcc, 0, v35, vcc
	v_mov_b64_e32 v[36:37], v[160:161]
	s_nop 0
	v_mov_b64_e32 v[34:35], v[176:177]
	v_mul_f32_e32 v41, 0x4b800000, v40
	v_cmp_gt_f32_e32 vcc, s97, v40
	s_nop 1
	v_cndmask_b32_e32 v40, v40, v41, vcc
	v_rsq_f32_e32 v40, v40
	s_nop 0
	v_mul_f32_e32 v41, 0x45800000, v40
	v_cndmask_b32_e32 v40, v40, v41, vcc
	s_waitcnt vmcnt(1)
	v_mul_f32_e32 v36, v36, v40
	v_mul_f32_e32 v37, v37, v40
	v_mul_f32_e32 v36, 0xbfb8aa3b, v36
	v_mul_f32_e32 v37, 0xbfb8aa3b, v37
	v_exp_f32_e32 v36, v36
	v_exp_f32_e32 v37, v37
	s_waitcnt vmcnt(0)
	v_pk_mul_f32 v[34:35], v[34:35], v[40:41] op_sel_hi:[1,0]
	v_add_f32_e32 v36, 1.0, v36
	v_add_f32_e32 v37, 1.0, v37
	v_rcp_f32_e32 v49, v36
	v_rcp_f32_e32 v50, v37
	v_mul_f32_e32 v40, 0xbfb8aa3b, v34
	v_mul_f32_e32 v41, 0xbfb8aa3b, v35
	v_fma_f32 v32, v38, v49, v32
	v_fmac_f32_e32 v33, v39, v50
	v_cmp_gt_f32_e32 vcc, s97, v32
	v_cmp_gt_f32_e64 s[14:15], s97, v33
	v_exp_f32_e32 v40, v40
	v_cndmask_b32_e64 v38, 0, 32, vcc
	v_cndmask_b32_e64 v39, 0, 32, s[14:15]
	v_ldexp_f32 v32, v32, v38
	v_exp_f32_e32 v41, v41
	v_ldexp_f32 v33, v33, v39
	v_log_f32_e32 v32, v32
	v_log_f32_e32 v33, v33
	v_add_f32_e32 v40, 1.0, v40
	v_add_f32_e32 v41, 1.0, v41
	v_rcp_f32_e32 v36, v40
	v_mul_f32_e32 v40, 0x3f317217, v32
	v_rcp_f32_e32 v37, v41
	v_mul_f32_e32 v41, 0x3f317217, v33
	v_fma_f32 v40, v32, s56, -v40
	v_fma_f32 v41, v33, s56, -v41
	v_fmac_f32_e32 v40, 0x3377d1cf, v32
	v_cndmask_b32_e32 v38, 0, v108, vcc
	v_fmac_f32_e32 v41, 0x3377d1cf, v33
	v_fmac_f32_e32 v40, 0x3f317217, v32
	v_cmp_lt_f32_e64 vcc, |v32|, s57
	v_fmac_f32_e32 v41, 0x3f317217, v33
	v_cndmask_b32_e64 v39, 0, v108, s[14:15]
	v_cndmask_b32_e32 v32, v32, v40, vcc
	v_cmp_lt_f32_e64 vcc, |v33|, s57
	v_sub_f32_e32 v32, v32, v38
	v_cvt_f16_f32_e32 v38, v32
	v_cndmask_b32_e32 v33, v33, v41, vcc
	v_sub_f32_e32 v33, v33, v39
	v_cvt_f16_f32_sdwa v39, v33 dst_sel:WORD_1 dst_unused:UNUSED_PAD src0_sel:DWORD
	v_pk_mul_f32 v[32:33], v[34:35], v[36:37]
	v_or_b32_e32 v49, v39, v38
	v_cvt_pk_bf16_f32 v114, v32, v33
.LBB0_1427:
	s_or_b64 exec, exec, s[18:19]
	v_cmp_gt_i32_e32 vcc, 16, v70
	v_mov_b32_e32 v32, 0
	v_lshlrev_b32_e32 v40, 2, v84
	v_mov_b32_e32 v36, 0
	v_mov_b32_e32 v37, 0
	v_mov_b32_e32 v38, 0
	v_mov_b32_e32 v39, 0
	v_mov_b32_e32 v71, 0
	v_mov_b32_e32 v99, 0
	v_mov_b32_e32 v103, 0
	v_mov_b32_e32 v98, 0
	s_and_saveexec_b64 s[14:15], vcc
	s_cbranch_execz .LBB0_1429
	v_readlane_b32 s18, v254, 11
	v_ashrrev_i32_e32 v71, 31, v70
	v_readlane_b32 s19, v254, 12
	v_mov_b32_e32 v41, v85
	s_nop 0
	v_lshl_add_u64 v[34:35], v[70:71], 2, s[18:19]
	global_load_dword v33, v[34:35], off
	v_readlane_b32 s18, v254, 14
	v_lshlrev_b64 v[34:35], 14, v[70:71]
	v_readlane_b32 s19, v254, 15

	v_lshl_add_u64 v[34:35], s[18:19], 0, v[34:35]
	s_lshl_b32 s18, s62, 2
	s_mov_b32 s19, s63
	v_lshl_add_u64 v[34:35], v[34:35], 0, s[18:19]
	v_lshl_add_u64 v[38:39], v[34:35], 0, v[40:41]
	v_add_co_u32_e32 v34, vcc, s54, v38
	s_mov_b64 s[18:19], 0x2000
	s_nop 0
	v_addc_co_u32_e32 v35, vcc, 0, v39, vcc
	v_add_co_u32_e32 v50, vcc, s55, v38
	v_lshl_add_u64 v[58:59], v[38:39], 0, s[18:19]
	s_nop 0
	v_addc_co_u32_e32 v51, vcc, 0, v39, vcc
	s_mov_b64 s[18:19], 0x3000
	global_load_dwordx4 v[34:37], v[34:35], off
	v_lshl_add_u64 v[38:39], v[38:39], 0, s[18:19]
	global_load_dwordx4 v[50:53], v[50:51], off
	s_nop 0
	global_load_dwordx4 v[54:57], v[38:39], off offset:16
	s_nop 0
	global_load_dwordx4 v[58:61], v[58:59], off offset:16
	s_waitcnt vmcnt(4)
	v_fmamk_f32 v33, v33, 0x3a800000, v86
	v_mul_f32_e32 v38, 0x4b800000, v33
	v_cmp_gt_f32_e32 vcc, s97, v33
	s_nop 1
	v_cndmask_b32_e32 v33, v33, v38, vcc
	v_rsq_f32_e32 v33, v33
	s_nop 0
	v_mul_f32_e32 v38, 0x45800000, v33
	v_cndmask_b32_e32 v38, v33, v38, vcc
	s_waitcnt vmcnt(3)
	v_mul_f32_e32 v33, v34, v38
	v_mul_f32_e32 v36, v36, v38
	s_waitcnt vmcnt(2)
	v_pk_mul_f32 v[50:51], v[50:51], v[38:39] op_sel_hi:[1,0]
	v_mul_f32_e32 v39, v35, v38
	v_pk_mul_f32 v[34:35], v[52:53], v[38:39] op_sel_hi:[1,0]
	v_mul_f32_e32 v37, v38, v37
	s_waitcnt vmcnt(1)
	v_mul_f32_e32 v41, v38, v54
	s_waitcnt vmcnt(0)
	v_pk_mul_f32 v[52:53], v[38:39], v[58:59] op_sel_hi:[0,1]
	v_mul_f32_e32 v58, v38, v55
	v_mul_f32_e32 v56, v38, v56
	v_pk_mul_f32 v[54:55], v[38:39], v[60:61] op_sel_hi:[0,1]
	v_mul_f32_e32 v38, v38, v57
	v_mul_f32_e32 v33, 0xbfb8aa3b, v33
	v_mul_f32_e32 v57, 0xbfb8aa3b, v39
	v_mul_f32_e32 v59, 0xbfb8aa3b, v36
	v_mul_f32_e32 v60, 0xbfb8aa3b, v37
	v_mul_f32_e32 v41, 0xbfb8aa3b, v41
	v_mul_f32_e32 v58, 0xbfb8aa3b, v58
	v_mul_f32_e32 v56, 0xbfb8aa3b, v56
	v_mul_f32_e32 v61, 0xbfb8aa3b, v38
	v_cvt_pk_bf16_f32 v36, v50, v51
	v_cvt_pk_bf16_f32 v37, v34, v35
	v_cvt_pk_bf16_f32 v38, v52, v53
	v_exp_f32_e32 v33, v33
	v_exp_f32_e32 v34, v57
	v_exp_f32_e32 v35, v59
	v_exp_f32_e32 v50, v60
	v_exp_f32_e32 v41, v41
	v_exp_f32_e32 v51, v58
	v_exp_f32_e32 v52, v56
	v_exp_f32_e32 v53, v61
	v_add_f32_e32 v33, 1.0, v33
	v_add_f32_e32 v34, 1.0, v34
	v_add_f32_e32 v35, 1.0, v35
	v_add_f32_e32 v50, 1.0, v50
	v_add_f32_e32 v41, 1.0, v41
	v_add_f32_e32 v51, 1.0, v51
	v_add_f32_e32 v52, 1.0, v52
	v_add_f32_e32 v53, 1.0, v53
	v_rcp_f32_e32 v33, v33
	v_rcp_f32_e32 v34, v34
	v_rcp_f32_e32 v35, v35
	v_rcp_f32_e32 v50, v50
	v_rcp_f32_e32 v41, v41
	v_rcp_f32_e32 v51, v51
	v_rcp_f32_e32 v52, v52
	v_rcp_f32_e32 v53, v53
	v_cvt_pk_bf16_f32 v39, v54, v55
	v_cvt_pk_bf16_f32 v71, v33, v34
	v_cvt_pk_bf16_f32 v99, v35, v50
	v_cvt_pk_bf16_f32 v103, v41, v51
	v_cvt_pk_bf16_f32 v98, v52, v53
